# G3/G5 residual epilogues: two load batches in flight (third batch lands in the first batch's already-stored accumulator registers)
# speedup vs baseline: 1.0116x; 1.0004x over previous
;     __device__ __forceinline__ void operator()(AccRef acc, const pg8::Unit& u, int wr, int wc, int fr, int fq) const {
;         const int lc = u.pn * 256 + wc * 64 + fq * 8;
;         const float* sb = (u.pm >= 128) ? srcS - (size_t)MP * 1024 : srcP;
; #pragma unroll
;         for (int ai = 0; ai < 2; ++ai)
; #pragma unroll
;             for (int m = 0; m < 4; ++m) {
;                 const size_t off = (size_t)(u.pm * 256 + ai * 128 + wr * 64 + m * 16 + fr) * 1024 + lc;
; #pragma unroll
;                 for (int bj = 0; bj < 2; ++bj)
; #pragma unroll
;                     for (int n = 0; n < 2; ++n) { const f32x4 s = *(const f32x4*)(sb + off + bj * 32 + n * 4); *(f32x4*)(dst + off + bj * 32 + n * 4) = s + acc[ai][bj][m][n]; }
;             }
;     }
.LBB0_557:
	v_lshl_add_u32 v142, s61, 8, v144
	v_lshl_or_b32 v140, s62, 8, v162
	v_ashrrev_i32_e32 v143, 31, v142
	v_ashrrev_i32_e32 v141, 31, v140
	s_cmpk_gt_i32 s61, 0x7f
	s_cselect_b32 s25, s59, s54
	s_cselect_b32 s24, s58, s55
	v_readlane_b32 s70, v254, 55
	v_readlane_b32 s80, v254, 57
	s_andn2_b64 vcc, exec, s[6:7]
	s_mov_b64 s[6:7], -1
	v_readlane_b32 s71, v254, 56
	v_readlane_b32 s81, v254, 58
	v_readlane_b32 s65, v254, 59
	s_movk_i32 s69, 0x2000
	v_lshlrev_b64 v[212:213], 10, v[142:143]
	v_lshl_add_u64 v[212:213], v[212:213], 0, v[140:141]
	v_lshlrev_b64 v[214:215], 2, v[212:213]
	v_lshl_add_u64 v[212:213], s[24:25], 0, v[214:215]
	v_lshl_add_u64 v[214:215], s[34:35], 0, v[214:215]
	global_load_dwordx4 v[164:167], v[212:213], off
	global_load_dwordx4 v[168:171], v[212:213], off offset:16
	global_load_dwordx4 v[172:175], v[212:213], off offset:128
	global_load_dwordx4 v[176:179], v[212:213], off offset:144
	v_add_u32_e32 v216, 0x10, v142
	v_ashrrev_i32_e32 v217, 31, v216
	v_lshlrev_b64 v[216:217], 10, v[216:217]
	v_lshl_add_u64 v[216:217], v[216:217], 0, v[140:141]
	v_lshlrev_b64 v[218:219], 2, v[216:217]
	v_lshl_add_u64 v[216:217], s[24:25], 0, v[218:219]
	v_lshl_add_u64 v[218:219], s[34:35], 0, v[218:219]
	global_load_dwordx4 v[180:183], v[216:217], off
	global_load_dwordx4 v[184:187], v[216:217], off offset:16
	global_load_dwordx4 v[188:191], v[216:217], off offset:128
	global_load_dwordx4 v[192:195], v[216:217], off offset:144
	s_waitcnt vmcnt(0)
	v_pk_add_f32 v[126:127], v[126:127], v[164:165]
	v_pk_add_f32 v[128:129], v[128:129], v[166:167]
	v_pk_add_f32 v[122:123], v[122:123], v[168:169]
	v_pk_add_f32 v[124:125], v[124:125], v[170:171]
	v_pk_add_f32 v[118:119], v[118:119], v[172:173]
	v_pk_add_f32 v[120:121], v[120:121], v[174:175]
	v_pk_add_f32 v[106:107], v[106:107], v[176:177]
	v_pk_add_f32 v[108:109], v[108:109], v[178:179]
	v_pk_add_f32 v[114:115], v[114:115], v[180:181]
	v_pk_add_f32 v[116:117], v[116:117], v[182:183]
	v_pk_add_f32 v[110:111], v[110:111], v[184:185]
	v_pk_add_f32 v[112:113], v[112:113], v[186:187]
	v_pk_add_f32 v[102:103], v[102:103], v[188:189]
	v_pk_add_f32 v[104:105], v[104:105], v[190:191]
	v_pk_add_f32 v[90:91], v[90:91], v[192:193]
	v_pk_add_f32 v[92:93], v[92:93], v[194:195]
	v_add_u32_e32 v220, 0x20, v142
	v_ashrrev_i32_e32 v221, 31, v220
	v_lshlrev_b64 v[220:221], 10, v[220:221]
	v_lshl_add_u64 v[220:221], v[220:221], 0, v[140:141]
	v_lshlrev_b64 v[222:223], 2, v[220:221]
	v_lshl_add_u64 v[220:221], s[24:25], 0, v[222:223]
	v_lshl_add_u64 v[222:223], s[34:35], 0, v[222:223]
	global_load_dwordx4 v[164:167], v[220:221], off
	global_load_dwordx4 v[168:171], v[220:221], off offset:16
	global_load_dwordx4 v[172:175], v[220:221], off offset:128
	global_load_dwordx4 v[176:179], v[220:221], off offset:144
	v_add_u32_e32 v224, 0x30, v142
	v_ashrrev_i32_e32 v225, 31, v224
	v_lshlrev_b64 v[224:225], 10, v[224:225]
	v_lshl_add_u64 v[224:225], v[224:225], 0, v[140:141]
	v_lshlrev_b64 v[226:227], 2, v[224:225]
	v_lshl_add_u64 v[224:225], s[24:25], 0, v[226:227]
	v_lshl_add_u64 v[226:227], s[34:35], 0, v[226:227]
	global_load_dwordx4 v[180:183], v[224:225], off
	global_load_dwordx4 v[184:187], v[224:225], off offset:16
	global_load_dwordx4 v[188:191], v[224:225], off offset:128
	global_load_dwordx4 v[192:195], v[224:225], off offset:144
	global_store_dwordx4 v[214:215], v[126:129], off
	global_store_dwordx4 v[214:215], v[122:125], off offset:16
	global_store_dwordx4 v[214:215], v[118:121], off offset:128
	global_store_dwordx4 v[214:215], v[106:109], off offset:144
	global_store_dwordx4 v[218:219], v[114:117], off
	global_store_dwordx4 v[218:219], v[110:113], off offset:16
	global_store_dwordx4 v[218:219], v[102:105], off offset:128
	global_store_dwordx4 v[218:219], v[90:93], off offset:144
	s_nop 1
	v_add_u32_e32 v228, 0x80, v142
	v_ashrrev_i32_e32 v229, 31, v228
	v_lshlrev_b64 v[228:229], 10, v[228:229]
	v_lshl_add_u64 v[228:229], v[228:229], 0, v[140:141]
	v_lshlrev_b64 v[230:231], 2, v[228:229]
	v_lshl_add_u64 v[228:229], s[24:25], 0, v[230:231]
	v_lshl_add_u64 v[230:231], s[34:35], 0, v[230:231]
	global_load_dwordx4 v[126:129], v[228:229], off
	global_load_dwordx4 v[122:125], v[228:229], off offset:16
	global_load_dwordx4 v[118:121], v[228:229], off offset:128
	global_load_dwordx4 v[106:109], v[228:229], off offset:144
	v_add_u32_e32 v232, 0x90, v142
	v_ashrrev_i32_e32 v233, 31, v232
	v_lshlrev_b64 v[232:233], 10, v[232:233]
	v_lshl_add_u64 v[232:233], v[232:233], 0, v[140:141]
	v_lshlrev_b64 v[234:235], 2, v[232:233]
	v_lshl_add_u64 v[232:233], s[24:25], 0, v[234:235]
	v_lshl_add_u64 v[234:235], s[34:35], 0, v[234:235]
	global_load_dwordx4 v[114:117], v[232:233], off
	global_load_dwordx4 v[110:113], v[232:233], off offset:16
	global_load_dwordx4 v[102:105], v[232:233], off offset:128
	global_load_dwordx4 v[90:93], v[232:233], off offset:144
	s_waitcnt vmcnt(16)
; #define PG8_BAR __builtin_amdgcn_s_barrier()
; template <class Epi, class Sched, bool ALIGN_EPI = false, bool SP2 = false>
; __device__ __forceinline__ void gemm_phase(PG8_LAS unsigned char* lds, const Gemm g, const Sched& S, const Epi& E) {
;     ...
;         if constexpr (ALIGN_EPI) { if (wr == 0) PG8_BAR; }
;         E(acc, cur, wr, wc, fr, fq); S.done(cur);
;         if (!has_next) break;
; #pragma unroll
;         for (int a = 0; a < 2; ++a)
; #pragma unroll
;             for (int b = 0; b < 2; ++b)
; #pragma unroll
;                 for (int m = 0; m < 4; ++m)
; #pragma unroll
;                     for (int n = 0; n < 2; ++n) acc[a][b][m][n] = (f32x4){0.f, 0.f, 0.f, 0.f};
;         cur = nxt; cA = nA; cB = nB; ++ui;
;         if constexpr (ALIGN_EPI) { if (wr == 1) PG8_BAR; }
;     __device__ __forceinline__ void operator()(AccRef acc, const pg8::Unit& u, int wr, int wc, int fr, int fq) const {
;         const int lc = u.pn * 256 + wc * 64 + fq * 8;
;         const float* sb = (u.pm >= 128) ? srcS - (size_t)MP * 1024 : srcP;
; #pragma unroll
;         for (int ai = 0; ai < 2; ++ai)
; #pragma unroll
;             for (int m = 0; m < 4; ++m) {
;                 const size_t off = (size_t)(u.pm * 256 + ai * 128 + wr * 64 + m * 16 + fr) * 1024 + lc;
; #pragma unroll
;                 for (int bj = 0; bj < 2; ++bj)
; #pragma unroll
;                     for (int n = 0; n < 2; ++n) { const f32x4 s = *(const f32x4*)(sb + off + bj * 32 + n * 4); *(f32x4*)(dst + off + bj * 32 + n * 4) = s + acc[ai][bj][m][n]; }
;             }
;     }
	v_pk_add_f32 v[98:99], v[98:99], v[164:165]
	v_pk_add_f32 v[100:101], v[100:101], v[166:167]
	v_pk_add_f32 v[94:95], v[94:95], v[168:169]
	v_pk_add_f32 v[96:97], v[96:97], v[170:171]
	v_pk_add_f32 v[86:87], v[86:87], v[172:173]
	v_pk_add_f32 v[88:89], v[88:89], v[174:175]
	v_pk_add_f32 v[74:75], v[74:75], v[176:177]
	v_pk_add_f32 v[76:77], v[76:77], v[178:179]
	v_pk_add_f32 v[82:83], v[82:83], v[180:181]
	v_pk_add_f32 v[84:85], v[84:85], v[182:183]
	v_pk_add_f32 v[78:79], v[78:79], v[184:185]
	v_pk_add_f32 v[80:81], v[80:81], v[186:187]
	v_pk_add_f32 v[70:71], v[70:71], v[188:189]
	v_pk_add_f32 v[72:73], v[72:73], v[190:191]
	v_pk_add_f32 v[66:67], v[66:67], v[192:193]
	v_pk_add_f32 v[68:69], v[68:69], v[194:195]
	v_add_u32_e32 v212, 0xa0, v142
	v_ashrrev_i32_e32 v213, 31, v212
	v_lshlrev_b64 v[212:213], 10, v[212:213]
	v_lshl_add_u64 v[212:213], v[212:213], 0, v[140:141]
	v_lshlrev_b64 v[214:215], 2, v[212:213]
	v_lshl_add_u64 v[212:213], s[24:25], 0, v[214:215]
	v_lshl_add_u64 v[214:215], s[34:35], 0, v[214:215]
	global_load_dwordx4 v[164:167], v[212:213], off
	global_load_dwordx4 v[168:171], v[212:213], off offset:16
	global_load_dwordx4 v[172:175], v[212:213], off offset:128
	global_load_dwordx4 v[176:179], v[212:213], off offset:144
	v_add_u32_e32 v216, 0xb0, v142
	v_ashrrev_i32_e32 v217, 31, v216
	v_lshlrev_b64 v[216:217], 10, v[216:217]
	v_lshl_add_u64 v[216:217], v[216:217], 0, v[140:141]
	v_lshlrev_b64 v[218:219], 2, v[216:217]
	v_lshl_add_u64 v[216:217], s[24:25], 0, v[218:219]
	v_lshl_add_u64 v[218:219], s[34:35], 0, v[218:219]
	global_load_dwordx4 v[180:183], v[216:217], off
	global_load_dwordx4 v[184:187], v[216:217], off offset:16
	global_load_dwordx4 v[188:191], v[216:217], off offset:128
	global_load_dwordx4 v[192:195], v[216:217], off offset:144
	global_store_dwordx4 v[222:223], v[98:101], off
	global_store_dwordx4 v[222:223], v[94:97], off offset:16
	global_store_dwordx4 v[222:223], v[86:89], off offset:128
	global_store_dwordx4 v[222:223], v[74:77], off offset:144
	global_store_dwordx4 v[226:227], v[82:85], off
	global_store_dwordx4 v[226:227], v[78:81], off offset:16
	global_store_dwordx4 v[226:227], v[70:73], off offset:128
	global_store_dwordx4 v[226:227], v[66:69], off offset:144
	s_waitcnt vmcnt(16)
	v_pk_add_f32 v[62:63], v[62:63], v[126:127]
	v_pk_add_f32 v[64:65], v[64:65], v[128:129]
	v_pk_add_f32 v[58:59], v[58:59], v[122:123]
	v_pk_add_f32 v[60:61], v[60:61], v[124:125]
	v_pk_add_f32 v[54:55], v[54:55], v[118:119]
	v_pk_add_f32 v[56:57], v[56:57], v[120:121]
	v_pk_add_f32 v[42:43], v[42:43], v[106:107]
	v_pk_add_f32 v[44:45], v[44:45], v[108:109]
	v_pk_add_f32 v[50:51], v[50:51], v[114:115]
	v_pk_add_f32 v[52:53], v[52:53], v[116:117]
	v_pk_add_f32 v[46:47], v[46:47], v[110:111]
	v_pk_add_f32 v[48:49], v[48:49], v[112:113]
	v_pk_add_f32 v[38:39], v[38:39], v[102:103]
	v_pk_add_f32 v[40:41], v[40:41], v[104:105]
	v_pk_add_f32 v[26:27], v[26:27], v[90:91]
	v_pk_add_f32 v[28:29], v[28:29], v[92:93]
	global_store_dwordx4 v[230:231], v[62:65], off
	global_store_dwordx4 v[230:231], v[58:61], off offset:16
	global_store_dwordx4 v[230:231], v[54:57], off offset:128
	global_store_dwordx4 v[230:231], v[42:45], off offset:144
	global_store_dwordx4 v[234:235], v[50:53], off
	global_store_dwordx4 v[234:235], v[46:49], off offset:16
	global_store_dwordx4 v[234:235], v[38:41], off offset:128
	global_store_dwordx4 v[234:235], v[26:29], off offset:144
	s_waitcnt vmcnt(16)
	v_pk_add_f32 v[34:35], v[34:35], v[164:165]
	v_pk_add_f32 v[36:37], v[36:37], v[166:167]
	v_pk_add_f32 v[30:31], v[30:31], v[168:169]
	v_pk_add_f32 v[32:33], v[32:33], v[170:171]
	v_pk_add_f32 v[22:23], v[22:23], v[172:173]
	v_pk_add_f32 v[24:25], v[24:25], v[174:175]
	v_pk_add_f32 v[10:11], v[10:11], v[176:177]
	v_pk_add_f32 v[12:13], v[12:13], v[178:179]
	v_pk_add_f32 v[18:19], v[18:19], v[180:181]
	v_pk_add_f32 v[20:21], v[20:21], v[182:183]
	v_pk_add_f32 v[14:15], v[14:15], v[184:185]
	v_pk_add_f32 v[16:17], v[16:17], v[186:187]
	v_pk_add_f32 v[6:7], v[6:7], v[188:189]
	v_pk_add_f32 v[8:9], v[8:9], v[190:191]
	v_pk_add_f32 v[2:3], v[2:3], v[192:193]
	v_pk_add_f32 v[4:5], v[4:5], v[194:195]
	global_store_dwordx4 v[214:215], v[34:37], off
	global_store_dwordx4 v[214:215], v[30:33], off offset:16
	global_store_dwordx4 v[214:215], v[22:25], off offset:128
	global_store_dwordx4 v[214:215], v[10:13], off offset:144
	global_store_dwordx4 v[218:219], v[18:21], off
	global_store_dwordx4 v[218:219], v[14:17], off offset:16
	global_store_dwordx4 v[218:219], v[6:9], off offset:128
	global_store_dwordx4 v[218:219], v[2:5], off offset:144
	s_cbranch_vccnz .LBB0_546
	s_andn2_b64 vcc, exec, s[8:9]
	s_cbranch_vccnz .LBB0_545
	s_barrier
	s_branch .LBB0_545

;     __device__ __forceinline__ void operator()(AccRef acc, const pg8::Unit& u, int wr, int wc, int fr, int fq) const {
;         const int lc = u.pn * 256 + wc * 64 + fq * 8;
;         const float* sb = (u.pm >= 128) ? srcS - (size_t)MP * 1024 : srcP;
; #pragma unroll
;         for (int ai = 0; ai < 2; ++ai)
; #pragma unroll
;             for (int m = 0; m < 4; ++m) {
;                 const size_t off = (size_t)(u.pm * 256 + ai * 128 + wr * 64 + m * 16 + fr) * 1024 + lc;
; #pragma unroll
;                 for (int bj = 0; bj < 2; ++bj)
; #pragma unroll
;                     for (int n = 0; n < 2; ++n) { const f32x4 s = *(const f32x4*)(sb + off + bj * 32 + n * 4); *(f32x4*)(dst + off + bj * 32 + n * 4) = s + acc[ai][bj][m][n]; }
;             }
;     }
.LBB0_650:
	v_lshl_add_u32 v142, s57, 8, v144
	v_lshl_or_b32 v140, s56, 8, v162
	v_ashrrev_i32_e32 v143, 31, v142
	v_ashrrev_i32_e32 v141, 31, v140
	s_andn2_b64 vcc, exec, s[4:5]
	s_mov_b64 s[4:5], -1
	v_lshlrev_b64 v[212:213], 10, v[142:143]
	v_lshl_add_u64 v[212:213], v[212:213], 0, v[140:141]
	v_lshlrev_b64 v[214:215], 2, v[212:213]
	v_lshl_add_u64 v[212:213], s[34:35], 0, v[214:215]
	v_lshl_add_u64 v[214:215], s[22:23], 0, v[214:215]
	global_load_dwordx4 v[164:167], v[212:213], off
	global_load_dwordx4 v[168:171], v[212:213], off offset:16
	global_load_dwordx4 v[172:175], v[212:213], off offset:128
	global_load_dwordx4 v[176:179], v[212:213], off offset:144
	v_add_u32_e32 v216, 0x10, v142
	v_ashrrev_i32_e32 v217, 31, v216
	v_lshlrev_b64 v[216:217], 10, v[216:217]
	v_lshl_add_u64 v[216:217], v[216:217], 0, v[140:141]
	v_lshlrev_b64 v[218:219], 2, v[216:217]
	v_lshl_add_u64 v[216:217], s[34:35], 0, v[218:219]
	v_lshl_add_u64 v[218:219], s[22:23], 0, v[218:219]
	global_load_dwordx4 v[180:183], v[216:217], off
	global_load_dwordx4 v[184:187], v[216:217], off offset:16
	global_load_dwordx4 v[188:191], v[216:217], off offset:128
	global_load_dwordx4 v[192:195], v[216:217], off offset:144
	s_waitcnt vmcnt(0)
	v_pk_add_f32 v[126:127], v[126:127], v[164:165]
	v_pk_add_f32 v[128:129], v[128:129], v[166:167]
	v_pk_add_f32 v[122:123], v[122:123], v[168:169]
	v_pk_add_f32 v[124:125], v[124:125], v[170:171]
	v_pk_add_f32 v[118:119], v[118:119], v[172:173]
	v_pk_add_f32 v[120:121], v[120:121], v[174:175]
	v_pk_add_f32 v[106:107], v[106:107], v[176:177]
	v_pk_add_f32 v[108:109], v[108:109], v[178:179]
	v_pk_add_f32 v[114:115], v[114:115], v[180:181]
	v_pk_add_f32 v[116:117], v[116:117], v[182:183]
	v_pk_add_f32 v[110:111], v[110:111], v[184:185]
	v_pk_add_f32 v[112:113], v[112:113], v[186:187]
	v_pk_add_f32 v[102:103], v[102:103], v[188:189]
	v_pk_add_f32 v[104:105], v[104:105], v[190:191]
	v_pk_add_f32 v[90:91], v[90:91], v[192:193]
	v_pk_add_f32 v[92:93], v[92:93], v[194:195]
	v_add_u32_e32 v220, 0x20, v142
	v_ashrrev_i32_e32 v221, 31, v220
	v_lshlrev_b64 v[220:221], 10, v[220:221]
	v_lshl_add_u64 v[220:221], v[220:221], 0, v[140:141]
	v_lshlrev_b64 v[222:223], 2, v[220:221]
	v_lshl_add_u64 v[220:221], s[34:35], 0, v[222:223]
	v_lshl_add_u64 v[222:223], s[22:23], 0, v[222:223]
	global_load_dwordx4 v[164:167], v[220:221], off
	global_load_dwordx4 v[168:171], v[220:221], off offset:16
	global_load_dwordx4 v[172:175], v[220:221], off offset:128
	global_load_dwordx4 v[176:179], v[220:221], off offset:144
	v_add_u32_e32 v224, 0x30, v142
	v_ashrrev_i32_e32 v225, 31, v224
	v_lshlrev_b64 v[224:225], 10, v[224:225]
	v_lshl_add_u64 v[224:225], v[224:225], 0, v[140:141]
	v_lshlrev_b64 v[226:227], 2, v[224:225]
	v_lshl_add_u64 v[224:225], s[34:35], 0, v[226:227]
	v_lshl_add_u64 v[226:227], s[22:23], 0, v[226:227]
	global_load_dwordx4 v[180:183], v[224:225], off
	global_load_dwordx4 v[184:187], v[224:225], off offset:16
	global_load_dwordx4 v[188:191], v[224:225], off offset:128
	global_load_dwordx4 v[192:195], v[224:225], off offset:144
	global_store_dwordx4 v[214:215], v[126:129], off
	global_store_dwordx4 v[214:215], v[122:125], off offset:16
	global_store_dwordx4 v[214:215], v[118:121], off offset:128
	global_store_dwordx4 v[214:215], v[106:109], off offset:144
	global_store_dwordx4 v[218:219], v[114:117], off
	global_store_dwordx4 v[218:219], v[110:113], off offset:16
	global_store_dwordx4 v[218:219], v[102:105], off offset:128
	global_store_dwordx4 v[218:219], v[90:93], off offset:144
	s_nop 1
	v_add_u32_e32 v228, 0x80, v142
	v_ashrrev_i32_e32 v229, 31, v228
	v_lshlrev_b64 v[228:229], 10, v[228:229]
	v_lshl_add_u64 v[228:229], v[228:229], 0, v[140:141]
	v_lshlrev_b64 v[230:231], 2, v[228:229]
	v_lshl_add_u64 v[228:229], s[34:35], 0, v[230:231]
	v_lshl_add_u64 v[230:231], s[22:23], 0, v[230:231]
	global_load_dwordx4 v[126:129], v[228:229], off
	global_load_dwordx4 v[122:125], v[228:229], off offset:16
	global_load_dwordx4 v[118:121], v[228:229], off offset:128
	global_load_dwordx4 v[106:109], v[228:229], off offset:144
	v_add_u32_e32 v232, 0x90, v142
	v_ashrrev_i32_e32 v233, 31, v232
	v_lshlrev_b64 v[232:233], 10, v[232:233]
	v_lshl_add_u64 v[232:233], v[232:233], 0, v[140:141]
	v_lshlrev_b64 v[234:235], 2, v[232:233]
	v_lshl_add_u64 v[232:233], s[34:35], 0, v[234:235]
	v_lshl_add_u64 v[234:235], s[22:23], 0, v[234:235]
	global_load_dwordx4 v[114:117], v[232:233], off
	global_load_dwordx4 v[110:113], v[232:233], off offset:16
	global_load_dwordx4 v[102:105], v[232:233], off offset:128
	global_load_dwordx4 v[90:93], v[232:233], off offset:144
	s_waitcnt vmcnt(16)
; #define PG8_BAR __builtin_amdgcn_s_barrier()
; template <class Epi, class Sched, bool ALIGN_EPI = false, bool SP2 = false>
; __device__ __forceinline__ void gemm_phase(PG8_LAS unsigned char* lds, const Gemm g, const Sched& S, const Epi& E) {
;     ...
;         if constexpr (ALIGN_EPI) { if (wr == 0) PG8_BAR; }
;         E(acc, cur, wr, wc, fr, fq); S.done(cur);
;         if (!has_next) break;
; #pragma unroll
;         for (int a = 0; a < 2; ++a)
; #pragma unroll
;             for (int b = 0; b < 2; ++b)
; #pragma unroll
;                 for (int m = 0; m < 4; ++m)
; #pragma unroll
;                     for (int n = 0; n < 2; ++n) acc[a][b][m][n] = (f32x4){0.f, 0.f, 0.f, 0.f};
;         cur = nxt; cA = nA; cB = nB; ++ui;
;         if constexpr (ALIGN_EPI) { if (wr == 1) PG8_BAR; }
;     __device__ __forceinline__ void operator()(AccRef acc, const pg8::Unit& u, int wr, int wc, int fr, int fq) const {
;         const int lc = u.pn * 256 + wc * 64 + fq * 8;
;         const float* sb = (u.pm >= 128) ? srcS - (size_t)MP * 1024 : srcP;
; #pragma unroll
;         for (int ai = 0; ai < 2; ++ai)
; #pragma unroll
;             for (int m = 0; m < 4; ++m) {
;                 const size_t off = (size_t)(u.pm * 256 + ai * 128 + wr * 64 + m * 16 + fr) * 1024 + lc;
; #pragma unroll
;                 for (int bj = 0; bj < 2; ++bj)
; #pragma unroll
;                     for (int n = 0; n < 2; ++n) { const f32x4 s = *(const f32x4*)(sb + off + bj * 32 + n * 4); *(f32x4*)(dst + off + bj * 32 + n * 4) = s + acc[ai][bj][m][n]; }
;             }
;     }
	v_pk_add_f32 v[98:99], v[98:99], v[164:165]
	v_pk_add_f32 v[100:101], v[100:101], v[166:167]
	v_pk_add_f32 v[94:95], v[94:95], v[168:169]
	v_pk_add_f32 v[96:97], v[96:97], v[170:171]
	v_pk_add_f32 v[86:87], v[86:87], v[172:173]
	v_pk_add_f32 v[88:89], v[88:89], v[174:175]
	v_pk_add_f32 v[74:75], v[74:75], v[176:177]
	v_pk_add_f32 v[76:77], v[76:77], v[178:179]
	v_pk_add_f32 v[82:83], v[82:83], v[180:181]
	v_pk_add_f32 v[84:85], v[84:85], v[182:183]
	v_pk_add_f32 v[78:79], v[78:79], v[184:185]
	v_pk_add_f32 v[80:81], v[80:81], v[186:187]
	v_pk_add_f32 v[70:71], v[70:71], v[188:189]
	v_pk_add_f32 v[72:73], v[72:73], v[190:191]
	v_pk_add_f32 v[66:67], v[66:67], v[192:193]
	v_pk_add_f32 v[68:69], v[68:69], v[194:195]
	v_add_u32_e32 v212, 0xa0, v142
	v_ashrrev_i32_e32 v213, 31, v212
	v_lshlrev_b64 v[212:213], 10, v[212:213]
	v_lshl_add_u64 v[212:213], v[212:213], 0, v[140:141]
	v_lshlrev_b64 v[214:215], 2, v[212:213]
	v_lshl_add_u64 v[212:213], s[34:35], 0, v[214:215]
	v_lshl_add_u64 v[214:215], s[22:23], 0, v[214:215]
	global_load_dwordx4 v[164:167], v[212:213], off
	global_load_dwordx4 v[168:171], v[212:213], off offset:16
	global_load_dwordx4 v[172:175], v[212:213], off offset:128
	global_load_dwordx4 v[176:179], v[212:213], off offset:144
	v_add_u32_e32 v216, 0xb0, v142
	v_ashrrev_i32_e32 v217, 31, v216
	v_lshlrev_b64 v[216:217], 10, v[216:217]
	v_lshl_add_u64 v[216:217], v[216:217], 0, v[140:141]
	v_lshlrev_b64 v[218:219], 2, v[216:217]
	v_lshl_add_u64 v[216:217], s[34:35], 0, v[218:219]
	v_lshl_add_u64 v[218:219], s[22:23], 0, v[218:219]
	global_load_dwordx4 v[180:183], v[216:217], off
	global_load_dwordx4 v[184:187], v[216:217], off offset:16
	global_load_dwordx4 v[188:191], v[216:217], off offset:128
	global_load_dwordx4 v[192:195], v[216:217], off offset:144
	global_store_dwordx4 v[222:223], v[98:101], off
	global_store_dwordx4 v[222:223], v[94:97], off offset:16
	global_store_dwordx4 v[222:223], v[86:89], off offset:128
	global_store_dwordx4 v[222:223], v[74:77], off offset:144
	global_store_dwordx4 v[226:227], v[82:85], off
	global_store_dwordx4 v[226:227], v[78:81], off offset:16
	global_store_dwordx4 v[226:227], v[70:73], off offset:128
	global_store_dwordx4 v[226:227], v[66:69], off offset:144
	s_waitcnt vmcnt(16)
	v_pk_add_f32 v[62:63], v[62:63], v[126:127]
	v_pk_add_f32 v[64:65], v[64:65], v[128:129]
	v_pk_add_f32 v[58:59], v[58:59], v[122:123]
	v_pk_add_f32 v[60:61], v[60:61], v[124:125]
	v_pk_add_f32 v[54:55], v[54:55], v[118:119]
	v_pk_add_f32 v[56:57], v[56:57], v[120:121]
	v_pk_add_f32 v[42:43], v[42:43], v[106:107]
	v_pk_add_f32 v[44:45], v[44:45], v[108:109]
	v_pk_add_f32 v[50:51], v[50:51], v[114:115]
	v_pk_add_f32 v[52:53], v[52:53], v[116:117]
	v_pk_add_f32 v[46:47], v[46:47], v[110:111]
	v_pk_add_f32 v[48:49], v[48:49], v[112:113]
	v_pk_add_f32 v[38:39], v[38:39], v[102:103]
	v_pk_add_f32 v[40:41], v[40:41], v[104:105]
	v_pk_add_f32 v[26:27], v[26:27], v[90:91]
	v_pk_add_f32 v[28:29], v[28:29], v[92:93]
	global_store_dwordx4 v[230:231], v[62:65], off
	global_store_dwordx4 v[230:231], v[58:61], off offset:16
	global_store_dwordx4 v[230:231], v[54:57], off offset:128
	global_store_dwordx4 v[230:231], v[42:45], off offset:144
	global_store_dwordx4 v[234:235], v[50:53], off
	global_store_dwordx4 v[234:235], v[46:49], off offset:16
	global_store_dwordx4 v[234:235], v[38:41], off offset:128
	global_store_dwordx4 v[234:235], v[26:29], off offset:144
	s_waitcnt vmcnt(16)
	v_pk_add_f32 v[34:35], v[34:35], v[164:165]
	v_pk_add_f32 v[36:37], v[36:37], v[166:167]
	v_pk_add_f32 v[30:31], v[30:31], v[168:169]
	v_pk_add_f32 v[32:33], v[32:33], v[170:171]
	v_pk_add_f32 v[22:23], v[22:23], v[172:173]
	v_pk_add_f32 v[24:25], v[24:25], v[174:175]
	v_pk_add_f32 v[10:11], v[10:11], v[176:177]
	v_pk_add_f32 v[12:13], v[12:13], v[178:179]
	v_pk_add_f32 v[18:19], v[18:19], v[180:181]
	v_pk_add_f32 v[20:21], v[20:21], v[182:183]
	v_pk_add_f32 v[14:15], v[14:15], v[184:185]
	v_pk_add_f32 v[16:17], v[16:17], v[186:187]
	v_pk_add_f32 v[6:7], v[6:7], v[188:189]
	v_pk_add_f32 v[8:9], v[8:9], v[190:191]
	v_pk_add_f32 v[2:3], v[2:3], v[192:193]
	v_pk_add_f32 v[4:5], v[4:5], v[194:195]
	global_store_dwordx4 v[214:215], v[34:37], off
	global_store_dwordx4 v[214:215], v[30:33], off offset:16
	global_store_dwordx4 v[214:215], v[22:25], off offset:128
	global_store_dwordx4 v[214:215], v[10:13], off offset:144
	global_store_dwordx4 v[218:219], v[18:21], off
	global_store_dwordx4 v[218:219], v[14:17], off offset:16
	global_store_dwordx4 v[218:219], v[6:9], off offset:128
	global_store_dwordx4 v[218:219], v[2:5], off offset:144
	s_cbranch_vccnz .LBB0_639
	s_andn2_b64 vcc, exec, s[0:1]
	s_cbranch_vccnz .LBB0_638
	s_barrier
	s_branch .LBB0_638
